# gate-sigmoid epilogue bias-load hoist on top of attention and K-loop changes (no priority change)
# speedup vs baseline: 1.0037x; 1.0003x over previous
.LBB0_798:
	v_lshl_or_b32 v130, s64, 8, v154
	v_ashrrev_i32_e32 v131, 31, v130
	v_lshl_add_u64 v[152:153], v[130:131], 2, s[10:11]
	global_load_dwordx4 v[134:137], v[152:153], off
	global_load_dwordx4 v[130:133], v[152:153], off offset:16
	global_load_dwordx4 v[206:209], v[152:153], off offset:512
	global_load_dwordx4 v[210:213], v[152:153], off offset:528
	s_lshl_b32 s17, s66, 3
	s_add_i32 s46, s17, s64
	s_ashr_i32 s47, s46, 31
	s_lshl_b64 s[46:47], s[46:47], 17
	v_lshl_add_u64 v[150:151], v[144:145], 0, s[46:47]
	v_add_co_u32_e32 v156, vcc, s36, v150
	s_waitcnt vmcnt(2)
	v_pk_add_f32 v[128:129], v[128:129], v[136:137]
	v_pk_add_f32 v[126:127], v[126:127], v[134:135]
	v_pk_add_f32 v[124:125], v[124:125], v[132:133]
	v_pk_add_f32 v[122:123], v[122:123], v[130:131]
	v_pk_add_f32 v[120:121], v[120:121], v[136:137]
	v_pk_add_f32 v[118:119], v[118:119], v[134:135]
	v_pk_add_f32 v[116:117], v[116:117], v[132:133]
	v_pk_add_f32 v[114:115], v[114:115], v[130:131]
	v_mul_f32_e32 v126, 0xbfb8aa3b, v126
	v_mul_f32_e32 v122, 0xbfb8aa3b, v122
	v_mul_f32_e32 v127, 0xbfb8aa3b, v127
	v_mul_f32_e32 v123, 0xbfb8aa3b, v123
	v_mul_f32_e32 v128, 0xbfb8aa3b, v128
	v_mul_f32_e32 v124, 0xbfb8aa3b, v124
	v_mul_f32_e32 v129, 0xbfb8aa3b, v129
	v_mul_f32_e32 v125, 0xbfb8aa3b, v125
	v_mul_f32_e32 v118, 0xbfb8aa3b, v118
	v_mul_f32_e32 v114, 0xbfb8aa3b, v114
	v_mul_f32_e32 v119, 0xbfb8aa3b, v119
	v_mul_f32_e32 v115, 0xbfb8aa3b, v115
	v_mul_f32_e32 v120, 0xbfb8aa3b, v120
	v_mul_f32_e32 v116, 0xbfb8aa3b, v116
	v_mul_f32_e32 v121, 0xbfb8aa3b, v121
	v_mul_f32_e32 v117, 0xbfb8aa3b, v117
	v_exp_f32_e32 v126, v126
	v_exp_f32_e32 v122, v122
	v_exp_f32_e32 v127, v127
	v_exp_f32_e32 v123, v123
	v_exp_f32_e32 v128, v128
	v_exp_f32_e32 v124, v124
	v_exp_f32_e32 v129, v129
	v_exp_f32_e32 v125, v125
	v_exp_f32_e32 v118, v118
	v_exp_f32_e32 v114, v114
	v_exp_f32_e32 v119, v119
	v_exp_f32_e32 v115, v115
	v_exp_f32_e32 v120, v120
	v_exp_f32_e32 v116, v116
	v_exp_f32_e32 v121, v121
	v_exp_f32_e32 v117, v117
	v_pk_add_f32 v[106:107], v[106:107], v[130:131]
	v_add_f32_e32 v126, 1.0, v126
	v_add_f32_e32 v122, 1.0, v122
	v_add_f32_e32 v127, 1.0, v127
	v_add_f32_e32 v123, 1.0, v123
	v_add_f32_e32 v128, 1.0, v128
	v_add_f32_e32 v124, 1.0, v124
	v_add_f32_e32 v129, 1.0, v129
	v_add_f32_e32 v125, 1.0, v125
	v_pk_add_f32 v[110:111], v[110:111], v[134:135]
	v_mul_f32_e32 v106, 0xbfb8aa3b, v106
	v_add_f32_e32 v118, 1.0, v118
	v_add_f32_e32 v114, 1.0, v114
	v_add_f32_e32 v119, 1.0, v119
	v_add_f32_e32 v115, 1.0, v115
	v_add_f32_e32 v120, 1.0, v120
	v_add_f32_e32 v116, 1.0, v116
	v_add_f32_e32 v121, 1.0, v121
	v_add_f32_e32 v117, 1.0, v117
	v_rcp_f32_e32 v126, v126
	v_rcp_f32_e32 v122, v122
	v_rcp_f32_e32 v127, v127
	v_rcp_f32_e32 v123, v123
	v_rcp_f32_e32 v128, v128
	v_rcp_f32_e32 v124, v124
	v_rcp_f32_e32 v129, v129
	v_rcp_f32_e32 v125, v125
	v_exp_f32_e32 v106, v106
	v_mul_f32_e32 v111, 0xbfb8aa3b, v111
	v_rcp_f32_e32 v118, v118
	v_rcp_f32_e32 v158, v114
	v_rcp_f32_e32 v119, v119
	v_rcp_f32_e32 v159, v115
	v_rcp_f32_e32 v120, v120
	v_rcp_f32_e32 v160, v116
	v_rcp_f32_e32 v121, v121
	v_rcp_f32_e32 v161, v117
	v_exp_f32_e32 v111, v111
	v_cvt_pk_bf16_f32 v114, v126, v127
	v_cvt_pk_bf16_f32 v115, v128, v129
	v_cvt_pk_bf16_f32 v116, v122, v123
	v_cvt_pk_bf16_f32 v117, v124, v125
	v_pk_add_f32 v[112:113], v[112:113], v[136:137]
	v_add_f32_e32 v106, 1.0, v106
	v_mul_f32_e32 v107, 0xbfb8aa3b, v107
	v_addc_co_u32_e32 v157, vcc, 0, v151, vcc
	v_cvt_pk_bf16_f32 v118, v118, v119
	v_cvt_pk_bf16_f32 v119, v120, v121
	v_cvt_pk_bf16_f32 v120, v158, v159
	v_cvt_pk_bf16_f32 v121, v160, v161
	global_store_dwordx4 v[150:151], v[114:117], off
	global_store_dwordx4 v[156:157], v[118:121], off
	v_exp_f32_e32 v107, v107
	v_rcp_f32_e32 v114, v106
	v_add_f32_e32 v106, 1.0, v111
	v_mul_f32_e32 v111, 0xbfb8aa3b, v112
	v_exp_f32_e32 v111, v111
	v_pk_add_f32 v[108:109], v[108:109], v[132:133]
	v_mul_f32_e32 v110, 0xbfb8aa3b, v110
	v_add_f32_e32 v107, 1.0, v107
	v_mul_f32_e32 v108, 0xbfb8aa3b, v108
	v_exp_f32_e32 v110, v110
	v_exp_f32_e32 v108, v108
	v_rcp_f32_e32 v112, v107
	v_add_f32_e32 v107, 1.0, v111
	v_mul_f32_e32 v111, 0xbfb8aa3b, v113
	v_mul_f32_e32 v109, 0xbfb8aa3b, v109
	v_exp_f32_e32 v111, v111
	v_exp_f32_e32 v109, v109
	v_add_f32_e32 v110, 1.0, v110
	v_add_f32_e32 v108, 1.0, v108
	v_pk_add_f32 v[98:99], v[98:99], v[130:131]
	v_rcp_f32_e32 v110, v110
	v_rcp_f32_e32 v106, v106
	v_rcp_f32_e32 v113, v108
	v_add_f32_e32 v108, 1.0, v111
	v_add_f32_e32 v109, 1.0, v109
	v_pk_add_f32 v[102:103], v[102:103], v[134:135]
	v_mul_f32_e32 v98, 0xbfb8aa3b, v98
	v_rcp_f32_e32 v107, v107
	v_rcp_f32_e32 v108, v108
	v_rcp_f32_e32 v109, v109
	v_exp_f32_e32 v98, v98
	v_mul_f32_e32 v103, 0xbfb8aa3b, v103
	v_exp_f32_e32 v103, v103
	v_cvt_pk_bf16_f32 v106, v110, v106
	v_add_co_u32_e32 v110, vcc, s15, v150
	v_cvt_pk_bf16_f32 v107, v107, v108
	v_cvt_pk_bf16_f32 v108, v114, v112
	v_cvt_pk_bf16_f32 v109, v113, v109
	v_addc_co_u32_e32 v111, vcc, 0, v151, vcc
	v_pk_add_f32 v[104:105], v[104:105], v[136:137]
	v_add_f32_e32 v98, 1.0, v98
	v_mul_f32_e32 v99, 0xbfb8aa3b, v99
	global_store_dwordx4 v[110:111], v[106:109], off
	v_exp_f32_e32 v99, v99
	v_pk_add_f32 v[100:101], v[100:101], v[132:133]
	v_rcp_f32_e32 v106, v98
	v_add_f32_e32 v98, 1.0, v103
	v_mul_f32_e32 v103, 0xbfb8aa3b, v104
	v_exp_f32_e32 v103, v103
	v_mul_f32_e32 v102, 0xbfb8aa3b, v102
	v_add_f32_e32 v99, 1.0, v99
	v_mul_f32_e32 v100, 0xbfb8aa3b, v100
	v_exp_f32_e32 v102, v102
	v_exp_f32_e32 v100, v100
	v_rcp_f32_e32 v104, v99
	v_add_f32_e32 v99, 1.0, v103
	v_mul_f32_e32 v103, 0xbfb8aa3b, v105
	v_mul_f32_e32 v101, 0xbfb8aa3b, v101
	v_exp_f32_e32 v103, v103
	v_exp_f32_e32 v101, v101
	v_add_f32_e32 v102, 1.0, v102
	v_add_f32_e32 v100, 1.0, v100
	v_pk_add_f32 v[90:91], v[90:91], v[130:131]
	v_rcp_f32_e32 v102, v102
	v_rcp_f32_e32 v98, v98
	v_rcp_f32_e32 v105, v100
	v_add_f32_e32 v100, 1.0, v103
	v_add_f32_e32 v101, 1.0, v101
	v_pk_add_f32 v[94:95], v[94:95], v[134:135]
	v_mul_f32_e32 v90, 0xbfb8aa3b, v90
	v_rcp_f32_e32 v99, v99
	v_rcp_f32_e32 v100, v100
	v_rcp_f32_e32 v101, v101
	v_exp_f32_e32 v90, v90
	v_mul_f32_e32 v95, 0xbfb8aa3b, v95
	v_exp_f32_e32 v95, v95
	v_cvt_pk_bf16_f32 v98, v102, v98
	v_add_co_u32_e32 v102, vcc, s33, v150
	v_cvt_pk_bf16_f32 v99, v99, v100
	v_cvt_pk_bf16_f32 v100, v106, v104
	v_cvt_pk_bf16_f32 v101, v105, v101
	v_addc_co_u32_e32 v103, vcc, 0, v151, vcc
	v_pk_add_f32 v[96:97], v[96:97], v[136:137]
	v_add_f32_e32 v90, 1.0, v90
	v_mul_f32_e32 v91, 0xbfb8aa3b, v91
	global_store_dwordx4 v[102:103], v[98:101], off
	v_exp_f32_e32 v91, v91
	v_pk_add_f32 v[92:93], v[92:93], v[132:133]
	v_rcp_f32_e32 v98, v90
	v_add_f32_e32 v90, 1.0, v95
	v_mul_f32_e32 v95, 0xbfb8aa3b, v96
	v_exp_f32_e32 v95, v95
	v_mul_f32_e32 v94, 0xbfb8aa3b, v94
	v_add_f32_e32 v91, 1.0, v91
	v_mul_f32_e32 v92, 0xbfb8aa3b, v92
	v_exp_f32_e32 v94, v94
	v_exp_f32_e32 v92, v92
	v_rcp_f32_e32 v96, v91
	v_add_f32_e32 v91, 1.0, v95
	v_mul_f32_e32 v95, 0xbfb8aa3b, v97
	v_mul_f32_e32 v93, 0xbfb8aa3b, v93
	v_exp_f32_e32 v95, v95
	v_exp_f32_e32 v93, v93
	v_add_f32_e32 v94, 1.0, v94
	v_add_f32_e32 v92, 1.0, v92
	v_pk_add_f32 v[82:83], v[82:83], v[130:131]
	v_rcp_f32_e32 v94, v94
	v_rcp_f32_e32 v90, v90
	v_rcp_f32_e32 v97, v92
	v_add_f32_e32 v92, 1.0, v95
	v_add_f32_e32 v93, 1.0, v93
	v_pk_add_f32 v[86:87], v[86:87], v[134:135]
	v_mul_f32_e32 v82, 0xbfb8aa3b, v82
	v_rcp_f32_e32 v91, v91
	v_rcp_f32_e32 v92, v92
	v_rcp_f32_e32 v93, v93
	v_exp_f32_e32 v82, v82
	v_mul_f32_e32 v87, 0xbfb8aa3b, v87
	v_exp_f32_e32 v87, v87
	v_cvt_pk_bf16_f32 v90, v94, v90
	v_add_co_u32_e32 v94, vcc, s37, v150
	v_cvt_pk_bf16_f32 v91, v91, v92
	v_cvt_pk_bf16_f32 v92, v98, v96
	v_cvt_pk_bf16_f32 v93, v97, v93
	v_addc_co_u32_e32 v95, vcc, 0, v151, vcc
	v_pk_add_f32 v[88:89], v[88:89], v[136:137]
	v_add_f32_e32 v82, 1.0, v82
	v_mul_f32_e32 v83, 0xbfb8aa3b, v83
	global_store_dwordx4 v[94:95], v[90:93], off
	v_exp_f32_e32 v83, v83
	v_pk_add_f32 v[84:85], v[84:85], v[132:133]
	v_rcp_f32_e32 v90, v82
	v_add_f32_e32 v82, 1.0, v87
	v_mul_f32_e32 v87, 0xbfb8aa3b, v88
	v_exp_f32_e32 v87, v87
	v_mul_f32_e32 v86, 0xbfb8aa3b, v86
	v_add_f32_e32 v83, 1.0, v83
	v_mul_f32_e32 v84, 0xbfb8aa3b, v84
	v_exp_f32_e32 v86, v86
	v_exp_f32_e32 v84, v84
	v_rcp_f32_e32 v88, v83
	v_add_f32_e32 v83, 1.0, v87
	v_mul_f32_e32 v87, 0xbfb8aa3b, v89
	v_mul_f32_e32 v85, 0xbfb8aa3b, v85
	v_exp_f32_e32 v87, v87
	v_exp_f32_e32 v85, v85
	v_add_f32_e32 v86, 1.0, v86
	v_add_f32_e32 v84, 1.0, v84
	v_pk_add_f32 v[74:75], v[74:75], v[130:131]
	v_rcp_f32_e32 v86, v86
	v_rcp_f32_e32 v82, v82
	v_rcp_f32_e32 v89, v84
	v_add_f32_e32 v84, 1.0, v87
	v_add_f32_e32 v85, 1.0, v85
	v_pk_add_f32 v[78:79], v[78:79], v[134:135]
	v_mul_f32_e32 v74, 0xbfb8aa3b, v74
	v_rcp_f32_e32 v83, v83
	v_rcp_f32_e32 v84, v84
	v_rcp_f32_e32 v85, v85
	v_exp_f32_e32 v74, v74
	v_mul_f32_e32 v79, 0xbfb8aa3b, v79
	v_exp_f32_e32 v79, v79
	v_cvt_pk_bf16_f32 v82, v86, v82
	v_add_co_u32_e32 v86, vcc, s55, v150
	v_cvt_pk_bf16_f32 v83, v83, v84
	v_cvt_pk_bf16_f32 v84, v90, v88
	v_cvt_pk_bf16_f32 v85, v89, v85
	v_addc_co_u32_e32 v87, vcc, 0, v151, vcc
	v_pk_add_f32 v[80:81], v[80:81], v[136:137]
	v_add_f32_e32 v74, 1.0, v74
	v_mul_f32_e32 v75, 0xbfb8aa3b, v75
	global_store_dwordx4 v[86:87], v[82:85], off
	v_exp_f32_e32 v75, v75
	v_pk_add_f32 v[76:77], v[76:77], v[132:133]
	v_rcp_f32_e32 v82, v74
	v_add_f32_e32 v74, 1.0, v79
	v_mul_f32_e32 v79, 0xbfb8aa3b, v80
	v_exp_f32_e32 v79, v79
	v_mul_f32_e32 v78, 0xbfb8aa3b, v78
	v_add_f32_e32 v75, 1.0, v75
	v_mul_f32_e32 v76, 0xbfb8aa3b, v76
	v_exp_f32_e32 v78, v78
	v_exp_f32_e32 v76, v76
	v_rcp_f32_e32 v80, v75
	v_add_f32_e32 v75, 1.0, v79
	v_mul_f32_e32 v79, 0xbfb8aa3b, v81
	v_mul_f32_e32 v77, 0xbfb8aa3b, v77
	v_exp_f32_e32 v79, v79
	v_exp_f32_e32 v77, v77
	v_add_f32_e32 v78, 1.0, v78
	v_add_f32_e32 v76, 1.0, v76
	v_pk_add_f32 v[62:63], v[62:63], v[130:131]
	v_rcp_f32_e32 v78, v78
	v_rcp_f32_e32 v74, v74
	v_rcp_f32_e32 v81, v76
	v_add_f32_e32 v76, 1.0, v79
	v_add_f32_e32 v77, 1.0, v77
	v_pk_add_f32 v[70:71], v[70:71], v[134:135]
	v_mul_f32_e32 v62, 0xbfb8aa3b, v62
	v_rcp_f32_e32 v75, v75
	v_rcp_f32_e32 v76, v76
	v_rcp_f32_e32 v77, v77
	v_exp_f32_e32 v62, v62
	v_mul_f32_e32 v71, 0xbfb8aa3b, v71
	v_exp_f32_e32 v71, v71
	v_cvt_pk_bf16_f32 v74, v78, v74
	v_add_co_u32_e32 v78, vcc, s44, v150
	v_cvt_pk_bf16_f32 v75, v75, v76
	v_cvt_pk_bf16_f32 v76, v82, v80
	v_cvt_pk_bf16_f32 v77, v81, v77
	v_addc_co_u32_e32 v79, vcc, 0, v151, vcc
	v_pk_add_f32 v[72:73], v[72:73], v[136:137]
	v_add_f32_e32 v62, 1.0, v62
	v_mul_f32_e32 v63, 0xbfb8aa3b, v63
	global_store_dwordx4 v[78:79], v[74:77], off
	v_exp_f32_e32 v63, v63
	v_pk_add_f32 v[64:65], v[64:65], v[132:133]
	v_rcp_f32_e32 v74, v62
	v_add_f32_e32 v62, 1.0, v71
	v_mul_f32_e32 v71, 0xbfb8aa3b, v72
	v_exp_f32_e32 v71, v71
	v_mul_f32_e32 v70, 0xbfb8aa3b, v70
	v_add_f32_e32 v63, 1.0, v63
	v_mul_f32_e32 v64, 0xbfb8aa3b, v64
	v_exp_f32_e32 v70, v70
	v_exp_f32_e32 v64, v64
	v_rcp_f32_e32 v72, v63
	v_add_f32_e32 v63, 1.0, v71
	v_mul_f32_e32 v71, 0xbfb8aa3b, v73
	v_mul_f32_e32 v65, 0xbfb8aa3b, v65
	v_exp_f32_e32 v71, v71
	v_exp_f32_e32 v65, v65
	v_add_f32_e32 v70, 1.0, v70
	v_add_f32_e32 v64, 1.0, v64
	v_rcp_f32_e32 v70, v70
	v_rcp_f32_e32 v62, v62
	v_rcp_f32_e32 v73, v64
	v_add_f32_e32 v64, 1.0, v71
	v_add_f32_e32 v65, 1.0, v65
	v_rcp_f32_e32 v63, v63
	v_rcp_f32_e32 v64, v64
	v_rcp_f32_e32 v65, v65
	v_cvt_pk_bf16_f32 v62, v70, v62
	v_add_co_u32_e32 v70, vcc, s30, v150
	v_cvt_pk_bf16_f32 v63, v63, v64
	v_cvt_pk_bf16_f32 v64, v74, v72
	v_cvt_pk_bf16_f32 v65, v73, v65
	v_addc_co_u32_e32 v71, vcc, 0, v151, vcc
	global_store_dwordx4 v[70:71], v[62:65], off
	s_nop 0
	s_waitcnt vmcnt(8)
	v_pk_add_f32 v[66:67], v[66:67], v[206:207]
	s_waitcnt vmcnt(8)
	v_pk_add_f32 v[58:59], v[58:59], v[210:211]
	v_mul_f32_e32 v67, 0xbfb8aa3b, v67
	v_mul_f32_e32 v58, 0xbfb8aa3b, v58
	v_exp_f32_e32 v58, v58
	v_exp_f32_e32 v67, v67
	v_pk_add_f32 v[68:69], v[68:69], v[208:209]
	v_mul_f32_e32 v59, 0xbfb8aa3b, v59
	v_add_f32_e32 v58, 1.0, v58
	v_exp_f32_e32 v59, v59
	v_rcp_f32_e32 v74, v58
	v_add_f32_e32 v58, 1.0, v67
	v_mul_f32_e32 v67, 0xbfb8aa3b, v68
	v_exp_f32_e32 v67, v67
	v_pk_add_f32 v[60:61], v[60:61], v[212:213]
	v_mul_f32_e32 v66, 0xbfb8aa3b, v66
	v_add_f32_e32 v59, 1.0, v59
	v_mul_f32_e32 v60, 0xbfb8aa3b, v60
	v_exp_f32_e32 v66, v66
	v_exp_f32_e32 v60, v60
	v_rcp_f32_e32 v68, v59
	v_add_f32_e32 v59, 1.0, v67
	v_mul_f32_e32 v67, 0xbfb8aa3b, v69
	v_mul_f32_e32 v61, 0xbfb8aa3b, v61
	v_exp_f32_e32 v67, v67
	v_exp_f32_e32 v61, v61
	v_add_f32_e32 v66, 1.0, v66
	v_add_f32_e32 v60, 1.0, v60
	v_pk_add_f32 v[50:51], v[50:51], v[210:211]
	v_rcp_f32_e32 v66, v66
	v_rcp_f32_e32 v58, v58
	v_rcp_f32_e32 v69, v60
	v_add_f32_e32 v60, 1.0, v67
	v_add_f32_e32 v61, 1.0, v61
	v_pk_add_f32 v[54:55], v[54:55], v[206:207]
	v_mul_f32_e32 v50, 0xbfb8aa3b, v50
	v_rcp_f32_e32 v59, v59
	v_rcp_f32_e32 v60, v60
	v_rcp_f32_e32 v61, v61
	v_exp_f32_e32 v50, v50
	v_mul_f32_e32 v55, 0xbfb8aa3b, v55
	v_exp_f32_e32 v55, v55
	v_cvt_pk_bf16_f32 v58, v66, v58
	v_add_co_u32_e32 v66, vcc, s39, v150
	v_cvt_pk_bf16_f32 v59, v59, v60
	v_cvt_pk_bf16_f32 v60, v74, v68
	v_cvt_pk_bf16_f32 v61, v69, v61
	v_addc_co_u32_e32 v67, vcc, 0, v151, vcc
	v_pk_add_f32 v[56:57], v[56:57], v[208:209]
	v_add_f32_e32 v50, 1.0, v50
	v_mul_f32_e32 v51, 0xbfb8aa3b, v51
	global_store_dwordx4 v[66:67], v[58:61], off
	v_exp_f32_e32 v51, v51
	v_pk_add_f32 v[52:53], v[52:53], v[212:213]
	v_rcp_f32_e32 v58, v50
	v_add_f32_e32 v50, 1.0, v55
	v_mul_f32_e32 v55, 0xbfb8aa3b, v56
	v_exp_f32_e32 v55, v55
	v_mul_f32_e32 v54, 0xbfb8aa3b, v54
	v_add_f32_e32 v51, 1.0, v51
	v_mul_f32_e32 v52, 0xbfb8aa3b, v52
	v_exp_f32_e32 v54, v54
	v_exp_f32_e32 v52, v52
	v_rcp_f32_e32 v56, v51
	v_add_f32_e32 v51, 1.0, v55
	v_mul_f32_e32 v55, 0xbfb8aa3b, v57
	v_mul_f32_e32 v53, 0xbfb8aa3b, v53
	v_exp_f32_e32 v55, v55
	v_exp_f32_e32 v53, v53
	v_add_f32_e32 v54, 1.0, v54
	v_add_f32_e32 v52, 1.0, v52
	v_pk_add_f32 v[42:43], v[42:43], v[210:211]
	v_rcp_f32_e32 v54, v54
	v_rcp_f32_e32 v50, v50
	v_rcp_f32_e32 v57, v52
	v_add_f32_e32 v52, 1.0, v55
	v_add_f32_e32 v53, 1.0, v53
	v_pk_add_f32 v[46:47], v[46:47], v[206:207]
	v_mul_f32_e32 v42, 0xbfb8aa3b, v42
	v_rcp_f32_e32 v51, v51
	v_rcp_f32_e32 v52, v52
	v_rcp_f32_e32 v53, v53
	v_exp_f32_e32 v42, v42
	v_mul_f32_e32 v47, 0xbfb8aa3b, v47
	v_exp_f32_e32 v47, v47
	v_cvt_pk_bf16_f32 v50, v54, v50
	v_add_co_u32_e32 v54, vcc, s34, v150
	v_cvt_pk_bf16_f32 v51, v51, v52
	v_cvt_pk_bf16_f32 v52, v58, v56
	v_cvt_pk_bf16_f32 v53, v57, v53
	v_addc_co_u32_e32 v55, vcc, 0, v151, vcc
	v_pk_add_f32 v[48:49], v[48:49], v[208:209]
	v_add_f32_e32 v42, 1.0, v42
	v_mul_f32_e32 v43, 0xbfb8aa3b, v43
	global_store_dwordx4 v[54:55], v[50:53], off
	v_exp_f32_e32 v43, v43
	v_pk_add_f32 v[44:45], v[44:45], v[212:213]
	v_rcp_f32_e32 v50, v42
	v_add_f32_e32 v42, 1.0, v47
	v_mul_f32_e32 v47, 0xbfb8aa3b, v48
	v_exp_f32_e32 v47, v47
	v_mul_f32_e32 v46, 0xbfb8aa3b, v46
	v_add_f32_e32 v43, 1.0, v43
	v_mul_f32_e32 v44, 0xbfb8aa3b, v44
	v_exp_f32_e32 v46, v46
	v_exp_f32_e32 v44, v44
	v_rcp_f32_e32 v48, v43
	v_add_f32_e32 v43, 1.0, v47
	v_mul_f32_e32 v47, 0xbfb8aa3b, v49
	v_mul_f32_e32 v45, 0xbfb8aa3b, v45
	v_exp_f32_e32 v47, v47
	v_exp_f32_e32 v45, v45
	v_add_f32_e32 v46, 1.0, v46
	v_add_f32_e32 v44, 1.0, v44
	v_pk_add_f32 v[34:35], v[34:35], v[210:211]
	v_rcp_f32_e32 v46, v46
	v_rcp_f32_e32 v42, v42
	v_rcp_f32_e32 v49, v44
	v_add_f32_e32 v44, 1.0, v47
	v_add_f32_e32 v45, 1.0, v45
	v_pk_add_f32 v[38:39], v[38:39], v[206:207]
	v_mul_f32_e32 v34, 0xbfb8aa3b, v34
	v_rcp_f32_e32 v43, v43
	v_rcp_f32_e32 v44, v44
	v_rcp_f32_e32 v45, v45
	v_exp_f32_e32 v34, v34
	v_mul_f32_e32 v39, 0xbfb8aa3b, v39
	v_exp_f32_e32 v39, v39
	v_cvt_pk_bf16_f32 v42, v46, v42
	v_add_co_u32_e32 v46, vcc, s14, v150
	v_cvt_pk_bf16_f32 v43, v43, v44
	v_cvt_pk_bf16_f32 v44, v50, v48
	v_cvt_pk_bf16_f32 v45, v49, v45
	v_addc_co_u32_e32 v47, vcc, 0, v151, vcc
	v_pk_add_f32 v[40:41], v[40:41], v[208:209]
	v_add_f32_e32 v34, 1.0, v34
	v_mul_f32_e32 v35, 0xbfb8aa3b, v35
	global_store_dwordx4 v[46:47], v[42:45], off
	v_exp_f32_e32 v35, v35
	v_pk_add_f32 v[36:37], v[36:37], v[212:213]
	v_rcp_f32_e32 v42, v34
	v_add_f32_e32 v34, 1.0, v39
	v_mul_f32_e32 v39, 0xbfb8aa3b, v40
	v_exp_f32_e32 v39, v39
	v_mul_f32_e32 v38, 0xbfb8aa3b, v38
	v_add_f32_e32 v35, 1.0, v35
	v_mul_f32_e32 v36, 0xbfb8aa3b, v36
	v_exp_f32_e32 v38, v38
	v_exp_f32_e32 v36, v36
	v_rcp_f32_e32 v40, v35
	v_add_f32_e32 v35, 1.0, v39
	v_mul_f32_e32 v39, 0xbfb8aa3b, v41
	v_mul_f32_e32 v37, 0xbfb8aa3b, v37
	v_exp_f32_e32 v39, v39
	v_exp_f32_e32 v37, v37
	v_add_f32_e32 v38, 1.0, v38
	v_add_f32_e32 v36, 1.0, v36
	v_pk_add_f32 v[26:27], v[26:27], v[210:211]
	v_rcp_f32_e32 v38, v38
	v_rcp_f32_e32 v34, v34
	v_rcp_f32_e32 v41, v36
	v_add_f32_e32 v36, 1.0, v39
	v_add_f32_e32 v37, 1.0, v37
	v_pk_add_f32 v[30:31], v[30:31], v[206:207]
	v_mul_f32_e32 v26, 0xbfb8aa3b, v26
	v_rcp_f32_e32 v35, v35
	v_rcp_f32_e32 v36, v36
	v_rcp_f32_e32 v37, v37
	v_exp_f32_e32 v26, v26
	v_mul_f32_e32 v31, 0xbfb8aa3b, v31
	v_exp_f32_e32 v31, v31
	v_cvt_pk_bf16_f32 v34, v38, v34
	v_add_co_u32_e32 v38, vcc, s3, v150
	v_cvt_pk_bf16_f32 v35, v35, v36
	v_cvt_pk_bf16_f32 v36, v42, v40
	v_cvt_pk_bf16_f32 v37, v41, v37
	v_addc_co_u32_e32 v39, vcc, 0, v151, vcc
	v_pk_add_f32 v[32:33], v[32:33], v[208:209]
	v_add_f32_e32 v26, 1.0, v26
	v_mul_f32_e32 v27, 0xbfb8aa3b, v27
	global_store_dwordx4 v[38:39], v[34:37], off
	v_exp_f32_e32 v27, v27
	v_pk_add_f32 v[28:29], v[28:29], v[212:213]
	v_rcp_f32_e32 v34, v26
	v_add_f32_e32 v26, 1.0, v31
	v_mul_f32_e32 v31, 0xbfb8aa3b, v32
	v_exp_f32_e32 v31, v31
	v_mul_f32_e32 v30, 0xbfb8aa3b, v30
	v_add_f32_e32 v27, 1.0, v27
	v_mul_f32_e32 v28, 0xbfb8aa3b, v28
	v_exp_f32_e32 v30, v30
	v_exp_f32_e32 v28, v28
	v_rcp_f32_e32 v32, v27
	v_add_f32_e32 v27, 1.0, v31
	v_mul_f32_e32 v31, 0xbfb8aa3b, v33
	v_mul_f32_e32 v29, 0xbfb8aa3b, v29
	v_exp_f32_e32 v31, v31
	v_exp_f32_e32 v29, v29
	v_add_f32_e32 v30, 1.0, v30
	v_add_f32_e32 v28, 1.0, v28
	v_pk_add_f32 v[18:19], v[18:19], v[210:211]
	v_rcp_f32_e32 v30, v30
	v_rcp_f32_e32 v26, v26
	v_rcp_f32_e32 v33, v28
	v_add_f32_e32 v28, 1.0, v31
	v_add_f32_e32 v29, 1.0, v29
	v_pk_add_f32 v[22:23], v[22:23], v[206:207]
	v_mul_f32_e32 v18, 0xbfb8aa3b, v18
	v_rcp_f32_e32 v27, v27
	v_rcp_f32_e32 v28, v28
	v_rcp_f32_e32 v29, v29
	v_exp_f32_e32 v18, v18
	v_mul_f32_e32 v23, 0xbfb8aa3b, v23
	v_exp_f32_e32 v23, v23
	v_cvt_pk_bf16_f32 v26, v30, v26
	v_add_co_u32_e32 v30, vcc, s31, v150
	v_cvt_pk_bf16_f32 v27, v27, v28
	v_cvt_pk_bf16_f32 v28, v34, v32
	v_cvt_pk_bf16_f32 v29, v33, v29
	v_addc_co_u32_e32 v31, vcc, 0, v151, vcc
	v_pk_add_f32 v[24:25], v[24:25], v[208:209]
	v_add_f32_e32 v18, 1.0, v18
	v_mul_f32_e32 v19, 0xbfb8aa3b, v19
	global_store_dwordx4 v[30:31], v[26:29], off
	v_exp_f32_e32 v19, v19
	v_pk_add_f32 v[20:21], v[20:21], v[212:213]
	v_rcp_f32_e32 v26, v18
	v_add_f32_e32 v18, 1.0, v23
	v_mul_f32_e32 v23, 0xbfb8aa3b, v24
	v_exp_f32_e32 v23, v23
	v_mul_f32_e32 v22, 0xbfb8aa3b, v22
	v_add_f32_e32 v19, 1.0, v19
	v_mul_f32_e32 v20, 0xbfb8aa3b, v20
	v_exp_f32_e32 v22, v22
	v_exp_f32_e32 v20, v20
	v_rcp_f32_e32 v24, v19
	v_add_f32_e32 v19, 1.0, v23
	v_mul_f32_e32 v23, 0xbfb8aa3b, v25
	v_mul_f32_e32 v21, 0xbfb8aa3b, v21
	v_exp_f32_e32 v23, v23
	v_exp_f32_e32 v21, v21
	v_add_f32_e32 v22, 1.0, v22
	v_add_f32_e32 v20, 1.0, v20
	v_pk_add_f32 v[10:11], v[10:11], v[210:211]
	v_rcp_f32_e32 v22, v22
	v_rcp_f32_e32 v18, v18
	v_rcp_f32_e32 v25, v20
	v_add_f32_e32 v20, 1.0, v23
	v_add_f32_e32 v21, 1.0, v21
	v_pk_add_f32 v[14:15], v[14:15], v[206:207]
	v_mul_f32_e32 v10, 0xbfb8aa3b, v10
	v_rcp_f32_e32 v19, v19
	v_rcp_f32_e32 v20, v20
	v_rcp_f32_e32 v21, v21
	v_exp_f32_e32 v10, v10
	v_mul_f32_e32 v15, 0xbfb8aa3b, v15
	v_exp_f32_e32 v15, v15
	v_cvt_pk_bf16_f32 v18, v22, v18
	v_add_co_u32_e32 v22, vcc, s38, v150
	v_cvt_pk_bf16_f32 v19, v19, v20
	v_cvt_pk_bf16_f32 v20, v26, v24
	v_cvt_pk_bf16_f32 v21, v25, v21
	v_addc_co_u32_e32 v23, vcc, 0, v151, vcc
	v_pk_add_f32 v[16:17], v[16:17], v[208:209]
	v_add_f32_e32 v10, 1.0, v10
	v_mul_f32_e32 v11, 0xbfb8aa3b, v11
	global_store_dwordx4 v[22:23], v[18:21], off
	v_exp_f32_e32 v11, v11
	v_pk_add_f32 v[12:13], v[12:13], v[212:213]
	v_rcp_f32_e32 v18, v10
	v_add_f32_e32 v10, 1.0, v15
	v_mul_f32_e32 v15, 0xbfb8aa3b, v16
	v_exp_f32_e32 v15, v15
	v_mul_f32_e32 v14, 0xbfb8aa3b, v14
	v_add_f32_e32 v11, 1.0, v11
	v_mul_f32_e32 v12, 0xbfb8aa3b, v12
	v_exp_f32_e32 v14, v14
	v_exp_f32_e32 v12, v12
	v_rcp_f32_e32 v16, v11
	v_add_f32_e32 v11, 1.0, v15
	v_mul_f32_e32 v15, 0xbfb8aa3b, v17
	v_mul_f32_e32 v13, 0xbfb8aa3b, v13
	v_exp_f32_e32 v15, v15
	v_exp_f32_e32 v13, v13
	v_add_f32_e32 v14, 1.0, v14
	v_add_f32_e32 v12, 1.0, v12
	v_pk_add_f32 v[2:3], v[2:3], v[210:211]
	v_rcp_f32_e32 v14, v14
	v_rcp_f32_e32 v10, v10
	v_rcp_f32_e32 v17, v12
	v_add_f32_e32 v12, 1.0, v15
	v_add_f32_e32 v13, 1.0, v13
	v_pk_add_f32 v[6:7], v[6:7], v[206:207]
	v_mul_f32_e32 v2, 0xbfb8aa3b, v2
	v_rcp_f32_e32 v11, v11
	v_rcp_f32_e32 v12, v12
	v_rcp_f32_e32 v13, v13
	v_exp_f32_e32 v2, v2
	v_mul_f32_e32 v7, 0xbfb8aa3b, v7
	v_exp_f32_e32 v7, v7
	v_cvt_pk_bf16_f32 v10, v14, v10
	v_add_co_u32_e32 v14, vcc, s35, v150
	v_cvt_pk_bf16_f32 v11, v11, v12
	v_cvt_pk_bf16_f32 v12, v18, v16
	v_cvt_pk_bf16_f32 v13, v17, v13
	v_addc_co_u32_e32 v15, vcc, 0, v151, vcc
	v_pk_add_f32 v[8:9], v[8:9], v[208:209]
	v_add_f32_e32 v2, 1.0, v2
	v_mul_f32_e32 v3, 0xbfb8aa3b, v3
	global_store_dwordx4 v[14:15], v[10:13], off
	v_exp_f32_e32 v3, v3
	v_mul_f32_e32 v6, 0xbfb8aa3b, v6
	v_rcp_f32_e32 v10, v2
	v_add_f32_e32 v2, 1.0, v7
	v_mul_f32_e32 v7, 0xbfb8aa3b, v8
	v_exp_f32_e32 v7, v7
	v_pk_add_f32 v[4:5], v[4:5], v[212:213]
	v_exp_f32_e32 v6, v6
	v_add_f32_e32 v3, 1.0, v3
	v_mul_f32_e32 v4, 0xbfb8aa3b, v4
	v_exp_f32_e32 v4, v4
	v_rcp_f32_e32 v8, v3
	v_add_f32_e32 v3, 1.0, v7
	v_mul_f32_e32 v7, 0xbfb8aa3b, v9
	v_mul_f32_e32 v5, 0xbfb8aa3b, v5
	v_exp_f32_e32 v7, v7
	v_exp_f32_e32 v5, v5
	v_add_f32_e32 v6, 1.0, v6
	v_rcp_f32_e32 v6, v6
	v_rcp_f32_e32 v2, v2
	v_add_f32_e32 v4, 1.0, v4
	v_rcp_f32_e32 v9, v4
	v_add_f32_e32 v4, 1.0, v7
	v_add_f32_e32 v5, 1.0, v5
	v_rcp_f32_e32 v3, v3
	v_rcp_f32_e32 v4, v4
	v_rcp_f32_e32 v5, v5
	v_cvt_pk_bf16_f32 v2, v6, v2
	v_add_co_u32_e32 v6, vcc, 0x1e000, v150
	v_cvt_pk_bf16_f32 v3, v3, v4
	s_nop 0
	v_addc_co_u32_e32 v7, vcc, 0, v151, vcc
	v_cvt_pk_bf16_f32 v4, v10, v8
	v_cvt_pk_bf16_f32 v5, v9, v5
	s_andn2_b64 vcc, exec, s[4:5]
	s_mov_b64 s[4:5], -1
	global_store_dwordx4 v[6:7], v[2:5], off
	s_cbranch_vccnz .LBB0_787
	s_andn2_b64 vcc, exec, s[8:9]
	s_cbranch_vccnz .LBB0_786
	s_barrier
	s_branch .LBB0_786
